# v10 + gla_b gate/gain pass: gain vector hoisted, 4 gate rows per iteration loaded together (4 round trips instead of 16)
# speedup vs baseline: 1.0009x; 1.0009x over previous
.LBB0_849:
	s_or_b64 exec, exec, s[86:87]
	s_lshl_b32 s23, s21, 17
	s_lshl_b64 s[0:1], s[8:9], 25
	s_lshl_b32 s76, s22, 9
	s_or_b32 s0, s0, s23
	s_and_b32 s22, s33, 0x300
	s_or_b32 s0, s0, s22
	s_lshl_b32 s86, s21, 16
	v_lshl_add_u64 v[10:11], v[162:163], 0, s[0:1]
	s_lshl_b64 s[0:1], s[8:9], 24
	s_or_b32 s0, s0, s86
	s_lshl_b32 s21, s21, 6
	s_or_b32 s0, s0, s22
	v_lshl_add_u64 v[12:13], v[164:165], 0, s[0:1]
	s_add_u32 s0, s21, s10
	s_addc_u32 s1, 0, s11
	s_waitcnt lgkmcnt(0)
	v_lshl_add_u64 v[0:1], s[0:1], 0, v[160:161]
	s_add_u32 s0, s91, s22
	v_lshlrev_b64 v[2:3], 11, v[0:1]
	s_addc_u32 s1, s74, 0
	v_lshl_add_u64 v[14:15], s[0:1], 0, v[2:3]
	s_add_u32 s0, s75, s22
	v_lshlrev_b64 v[0:1], 10, v[0:1]
	s_addc_u32 s1, s78, 0
	v_lshl_add_u64 v[8:9], v[154:155], 0, s[76:77]
	global_load_dwordx4 v[236:239], v[8:9], off
	global_load_dwordx4 v[240:243], v[8:9], off offset:16
	s_waitcnt vmcnt(0)
	v_lshl_add_u64 v[16:17], s[0:1], 0, v[0:1]
	s_mov_b32 s0, 0
	v_mov_b32_e32 v24, v123
.LBB0_850:
	v_lshl_add_u64 v[0:1], v[16:17], 0, v[102:103]
	v_add_co_u32_e32 v214, vcc, 0x1000, v0
	s_nop 1
	v_addc_co_u32_e32 v215, vcc, 0, v1, vcc
	v_add_co_u32_e32 v216, vcc, 0x3000, v0
	s_nop 1
	v_addc_co_u32_e32 v217, vcc, 0, v1, vcc
	global_load_dwordx4 v[198:201], v[214:215], off offset:-4096
	global_load_dwordx4 v[202:205], v[214:215], off
	global_load_dwordx4 v[206:209], v[216:217], off offset:-4096
	global_load_dwordx4 v[210:213], v[216:217], off
	ds_read_b128 v[2:5], v24
	v_mov_b64_e32 v[20:21], v[240:241]
	v_mov_b64_e32 v[22:23], v[242:243]
	v_mov_b64_e32 v[26:27], v[236:237]
	v_mov_b64_e32 v[28:29], v[238:239]
	s_waitcnt vmcnt(3)
	v_mov_b64_e32 v[30:31], v[198:199]
	v_mov_b64_e32 v[32:33], v[200:201]
	v_add_u32_e32 v18, s0, v121
	ds_read2_b32 v[0:1], v18 offset1:4
	ds_read2_b32 v[18:19], v18 offset0:8 offset1:12
	s_waitcnt lgkmcnt(2)
	v_lshlrev_b32_e32 v6, 16, v2
	v_and_b32_e32 v7, 0xffff0000, v2
	s_mov_b32 s1, 0x1ab82000
	s_waitcnt lgkmcnt(1)
	v_pk_mul_f32 v[6:7], v[0:1], v[6:7] op_sel_hi:[0,1]
	s_add_i32 s0, s0, 64
	v_lshl_add_u64 v[16:17], v[16:17], 0, s[94:95]
	s_cmpk_lg_i32 s0, 0x100
	v_pk_mul_f32 v[6:7], v[26:27], v[6:7]
	v_lshlrev_b32_e32 v26, 16, v30
	v_and_b32_e32 v27, 0xffff0000, v30
	v_pk_mul_f32 v[6:7], v[6:7], v[26:27]
	v_lshlrev_b32_e32 v26, 16, v31
	v_cvt_pk_bf16_f32 v2, v6, v7
	v_lshlrev_b32_e32 v6, 16, v3
	v_and_b32_e32 v7, 0xffff0000, v3
	v_pk_mul_f32 v[6:7], v[0:1], v[6:7] op_sel_hi:[0,1]
	v_pk_mul_f32 v[6:7], v[28:29], v[6:7]
	v_and_b32_e32 v27, 0xffff0000, v31
	v_pk_mul_f32 v[6:7], v[6:7], v[26:27]
	ds_read_b128 v[26:29], v24 offset:1088
	v_cvt_pk_bf16_f32 v3, v6, v7
	v_lshlrev_b32_e32 v6, 16, v4
	v_and_b32_e32 v7, 0xffff0000, v4
	v_pk_mul_f32 v[6:7], v[0:1], v[6:7] op_sel_hi:[0,1]
	v_pk_mul_f32 v[6:7], v[6:7], v[20:21]
	v_lshlrev_b32_e32 v20, 16, v32
	v_and_b32_e32 v21, 0xffff0000, v32
	v_pk_mul_f32 v[6:7], v[6:7], v[20:21]
	v_lshlrev_b32_e32 v20, 16, v33
	v_cvt_pk_bf16_f32 v4, v6, v7
	v_lshlrev_b32_e32 v6, 16, v5
	v_and_b32_e32 v7, 0xffff0000, v5
	v_pk_mul_f32 v[6:7], v[0:1], v[6:7] op_sel_hi:[0,1]
	v_pk_mul_f32 v[6:7], v[6:7], v[22:23]
	v_and_b32_e32 v21, 0xffff0000, v33
	v_pk_mul_f32 v[6:7], v[6:7], v[20:21]
	v_lshl_add_u64 v[20:21], v[12:13], 0, v[102:103]
	v_cvt_pk_bf16_f32 v5, v6, v7
	v_lshl_add_u64 v[6:7], v[14:15], 0, v[102:103]
	global_store_dwordx4 v[6:7], v[2:5], off
	v_mov_b64_e32 v[30:31], v[240:241]
	v_mov_b64_e32 v[32:33], v[242:243]
	v_mov_b64_e32 v[34:35], v[236:237]
	v_mov_b64_e32 v[36:37], v[238:239]
	v_add_co_u32_e32 v4, vcc, s1, v20
	s_waitcnt lgkmcnt(0)
	v_lshlrev_b32_e32 v2, 16, v26
	v_addc_co_u32_e32 v5, vcc, 0, v21, vcc
	s_waitcnt vmcnt(3)
	v_mov_b64_e32 v[38:39], v[202:203]
	v_mov_b64_e32 v[40:41], v[204:205]
	v_and_b32_e32 v3, 0xffff0000, v26
	v_mov_b32_e32 v6, v1
	v_pk_mul_f32 v[0:1], v[6:7], v[2:3] op_sel_hi:[0,1]
	s_mov_b32 s1, 0x7702000
	v_lshl_add_u64 v[12:13], v[12:13], 0, s[94:95]
	v_lshl_add_u64 v[14:15], v[14:15], 0, s[82:83]
	v_pk_mul_f32 v[0:1], v[34:35], v[0:1]
	v_lshlrev_b32_e32 v2, 16, v38
	v_and_b32_e32 v3, 0xffff0000, v38
	v_pk_mul_f32 v[0:1], v[0:1], v[2:3]
	v_lshlrev_b32_e32 v2, 16, v27
	v_and_b32_e32 v3, 0xffff0000, v27
	v_pk_mul_f32 v[2:3], v[6:7], v[2:3] op_sel_hi:[0,1]
	v_pk_mul_f32 v[2:3], v[36:37], v[2:3]
	v_lshlrev_b32_e32 v22, 16, v39
	v_and_b32_e32 v23, 0xffff0000, v39
	v_pk_mul_f32 v[2:3], v[2:3], v[22:23]
	v_cvt_pk_bf16_f32 v0, v0, v1
	v_cvt_pk_bf16_f32 v1, v2, v3
	v_lshlrev_b32_e32 v2, 16, v28
	v_and_b32_e32 v3, 0xffff0000, v28
	v_pk_mul_f32 v[2:3], v[6:7], v[2:3] op_sel_hi:[0,1]
	v_pk_mul_f32 v[2:3], v[2:3], v[30:31]
	v_lshlrev_b32_e32 v22, 16, v40
	v_and_b32_e32 v23, 0xffff0000, v40
	v_pk_mul_f32 v[2:3], v[2:3], v[22:23]
	v_lshlrev_b32_e32 v22, 16, v29
	v_and_b32_e32 v23, 0xffff0000, v29
	v_pk_mul_f32 v[6:7], v[6:7], v[22:23] op_sel_hi:[0,1]
	v_pk_mul_f32 v[6:7], v[6:7], v[32:33]
	v_lshlrev_b32_e32 v22, 16, v41
	v_and_b32_e32 v23, 0xffff0000, v41
	v_pk_mul_f32 v[6:7], v[6:7], v[22:23]
	v_lshl_add_u64 v[22:23], v[10:11], 0, v[102:103]
	v_cvt_pk_bf16_f32 v2, v2, v3
	v_cvt_pk_bf16_f32 v3, v6, v7
	v_add_co_u32_e32 v6, vcc, s1, v22
	s_mov_b32 s1, 0x7704000
	s_nop 0
	v_addc_co_u32_e32 v7, vcc, 0, v23, vcc
	global_store_dwordx4 v[6:7], v[0:3], off offset:1024
	ds_read_b128 v[0:3], v24 offset:2176
	v_mov_b64_e32 v[26:27], v[240:241]
	v_mov_b64_e32 v[28:29], v[242:243]
	v_mov_b64_e32 v[30:31], v[236:237]
	v_mov_b64_e32 v[32:33], v[238:239]
	s_nop 0
	s_waitcnt vmcnt(3)
	v_mov_b64_e32 v[4:5], v[206:207]
	v_mov_b64_e32 v[6:7], v[208:209]
	v_lshl_add_u64 v[10:11], v[10:11], 0, s[82:83]
	s_waitcnt lgkmcnt(0)
	v_lshlrev_b32_e32 v34, 16, v0
	v_and_b32_e32 v35, 0xffff0000, v0
	v_pk_mul_f32 v[34:35], v[18:19], v[34:35] op_sel_hi:[0,1]
	v_pk_mul_f32 v[30:31], v[30:31], v[34:35]
	v_lshlrev_b32_e32 v34, 16, v4
	v_and_b32_e32 v35, 0xffff0000, v4
	v_pk_mul_f32 v[30:31], v[30:31], v[34:35]
	v_lshlrev_b32_e32 v4, 16, v5
	v_cvt_pk_bf16_f32 v0, v30, v31
	v_lshlrev_b32_e32 v30, 16, v1
	v_and_b32_e32 v31, 0xffff0000, v1
	v_pk_mul_f32 v[30:31], v[18:19], v[30:31] op_sel_hi:[0,1]
	v_pk_mul_f32 v[30:31], v[32:33], v[30:31]
	v_and_b32_e32 v5, 0xffff0000, v5
	v_pk_mul_f32 v[4:5], v[30:31], v[4:5]
	s_nop 0
	v_cvt_pk_bf16_f32 v1, v4, v5
	v_lshlrev_b32_e32 v4, 16, v2
	v_and_b32_e32 v5, 0xffff0000, v2
	v_pk_mul_f32 v[4:5], v[18:19], v[4:5] op_sel_hi:[0,1]
	v_pk_mul_f32 v[4:5], v[4:5], v[26:27]
	v_lshlrev_b32_e32 v26, 16, v6
	v_and_b32_e32 v27, 0xffff0000, v6
	v_pk_mul_f32 v[4:5], v[4:5], v[26:27]
	v_lshlrev_b32_e32 v6, 16, v7
	v_cvt_pk_bf16_f32 v2, v4, v5
	v_lshlrev_b32_e32 v4, 16, v3
	v_and_b32_e32 v5, 0xffff0000, v3
	v_pk_mul_f32 v[4:5], v[18:19], v[4:5] op_sel_hi:[0,1]
	v_pk_mul_f32 v[4:5], v[4:5], v[28:29]
	v_and_b32_e32 v7, 0xffff0000, v7
	v_pk_mul_f32 v[4:5], v[4:5], v[6:7]
	v_mov_b32_e32 v18, v19
	v_cvt_pk_bf16_f32 v3, v4, v5
	v_add_co_u32_e32 v4, vcc, s1, v22
	s_mov_b32 s1, 0x1ab83000
	s_nop 0
	v_addc_co_u32_e32 v5, vcc, 0, v23, vcc
	v_add_co_u32_e32 v20, vcc, s1, v20
	global_store_dwordx4 v[4:5], v[0:3], off offset:1024
	s_nop 0
	v_addc_co_u32_e32 v21, vcc, 0, v21, vcc
	ds_read_b128 v[4:7], v24 offset:3264
	v_mov_b64_e32 v[0:1], v[240:241]
	v_mov_b64_e32 v[2:3], v[242:243]
	v_mov_b64_e32 v[26:27], v[236:237]
	v_mov_b64_e32 v[28:29], v[238:239]
	s_waitcnt vmcnt(3)
	v_mov_b64_e32 v[30:31], v[210:211]
	v_mov_b64_e32 v[32:33], v[212:213]
	v_add_u32_e32 v24, 0x1100, v24
	s_waitcnt lgkmcnt(0)
	v_lshlrev_b32_e32 v20, 16, v4
	v_and_b32_e32 v21, 0xffff0000, v4
	v_pk_mul_f32 v[20:21], v[18:19], v[20:21] op_sel_hi:[0,1]
	v_pk_mul_f32 v[20:21], v[26:27], v[20:21]
	v_lshlrev_b32_e32 v26, 16, v30
	v_and_b32_e32 v27, 0xffff0000, v30
	v_pk_mul_f32 v[20:21], v[20:21], v[26:27]
	v_lshlrev_b32_e32 v26, 16, v31
	v_cvt_pk_bf16_f32 v4, v20, v21
	v_lshlrev_b32_e32 v20, 16, v5
	v_and_b32_e32 v21, 0xffff0000, v5
	v_pk_mul_f32 v[20:21], v[18:19], v[20:21] op_sel_hi:[0,1]
	v_pk_mul_f32 v[20:21], v[28:29], v[20:21]
	v_and_b32_e32 v27, 0xffff0000, v31
	v_pk_mul_f32 v[20:21], v[20:21], v[26:27]
	s_nop 0
	v_cvt_pk_bf16_f32 v5, v20, v21
	v_lshlrev_b32_e32 v20, 16, v6
	v_and_b32_e32 v21, 0xffff0000, v6
	v_pk_mul_f32 v[20:21], v[18:19], v[20:21] op_sel_hi:[0,1]
	v_pk_mul_f32 v[0:1], v[20:21], v[0:1]
	v_lshlrev_b32_e32 v20, 16, v32
	v_and_b32_e32 v21, 0xffff0000, v32
	v_pk_mul_f32 v[0:1], v[0:1], v[20:21]
	s_nop 0
	v_cvt_pk_bf16_f32 v6, v0, v1
	v_lshlrev_b32_e32 v0, 16, v7
	v_and_b32_e32 v1, 0xffff0000, v7
	v_pk_mul_f32 v[0:1], v[18:19], v[0:1] op_sel_hi:[0,1]
	v_pk_mul_f32 v[0:1], v[0:1], v[2:3]
	v_lshlrev_b32_e32 v2, 16, v33
	v_and_b32_e32 v3, 0xffff0000, v33
	v_pk_mul_f32 v[0:1], v[0:1], v[2:3]
	s_nop 0
	v_cvt_pk_bf16_f32 v7, v0, v1
	v_add_co_u32_e32 v0, vcc, 0x7706000, v22
	s_nop 1
	v_addc_co_u32_e32 v1, vcc, 0, v23, vcc
	global_store_dwordx4 v[0:1], v[4:7], off offset:1024
	s_cbranch_scc1 .LBB0_850
	v_readlane_b32 s0, v245, 19
	s_add_i32 s33, s33, s92
	s_add_i32 s73, s73, s0
	s_cmpk_gt_i32 s33, 0x7ff
	v_lshl_add_u64 v[156:157], v[156:157], 0, s[80:81]
	v_readlane_b32 s1, v245, 20
	s_cbranch_scc0 .LBB0_845
